# DMA stage loads issued before ds_reads in every load step, now also in the EpiF32 loop
# baseline (speedup 1.0000x reference)
; #define PG8_STAGE(bufoff, gbase, voff) do { _Pragma("unroll") for (int _i = 0; _i < 2; ++_i) \
;         __builtin_amdgcn_global_load_lds((const unsigned*)((const char*)(gbase) + (voff)[_i]), (LAS unsigned*)(lds + (bufoff) + ldsw + _i * 8192), 16, 0, 0); } while (0)
; #define PG8_LDA(dst, b, h) do { _Pragma("unroll") for (int m = 0; m < 4; ++m) _Pragma("unroll") for (int k = 0; k < 2; ++k) dst[m][k] = *(const LAS bf16x8*)(lds + PG8_SA(b, h) + aoff + m * 2048 + k * 1024); } while (0)
; #define PG8_LDB(dst, b, h) do { _Pragma("unroll") for (int n = 0; n < 2; ++n) _Pragma("unroll") for (int k = 0; k < 2; ++k) dst[n][k] = *(const LAS bf16x8*)(lds + PG8_SB(b, h) + boff + n * 2048 + k * 1024); } while (0)
; #define PG8_MMA(ai, bj, At, Bt) do { __builtin_amdgcn_s_setprio(1); _Pragma("unroll") for (int m = 0; m < 4; ++m) _Pragma("unroll") for (int n = 0; n < 2; ++n) _Pragma("unroll") for (int k = 0; k < 2; ++k) \
;         acc[ai][bj][m][n] = __builtin_amdgcn_mfma_f32_16x16x32_bf16(Bt[n][k], At[m][k], acc[ai][bj][m][n], 0, 0, 0); __builtin_amdgcn_s_setprio(0); } while (0)
; #define PG8_WAIT_V(n) asm volatile("s_waitcnt vmcnt(" #n ")" ::: "memory")
; #define PG8_WAIT_L(n) asm volatile("s_waitcnt lgkmcnt(" #n ")" ::: "memory")
; template <class Epi>
; __device__ __forceinline__ void gemm_phase(LAS unsigned char* lds, const Gemm g, const Sched& S, const Epi& E) {
;     ...
;         for (int t = 0; t < nt; t += 2) {
;             const bool last = (t == nt - 2);
;             const char* a1 = cA + (size_t)(t + 1) * kstep;
;             const char* a2 = last ? nA : cA + (size_t)(t + 2) * kstep; const char* b2 = last ? nB : cB + (size_t)(t + 2) * kstep;
;             const char* a3 = a2 + kstep; const char* b3 = b2 + kstep;
;             PG8_LDB(B0, 0, 0); PG8_SCHED; PG8_LDA(At, 0, 0); PG8_STAGE(PG8_SA(1, 1), a1 + hstepA, voffA);
;             PG8_WAIT_L(8); PG8_BAR; PG8_WAIT_L(0); PG8_MMA(0, 0, At, B0); PG8_BAR; PG8_SCHED;
;             PG8_LDB(B1, 0, 1); PG8_STAGE(PG8_SB(0, 0), b2, voffB);
;             PG8_BAR; PG8_WAIT_L(0); PG8_MMA(0, 1, At, B1); PG8_BAR;
;             PG8_LDA(At, 0, 1); PG8_STAGE(PG8_SA(0, 0), a2, voffA);
;             PG8_BAR; PG8_WAIT_L(0); PG8_MMA(1, 0, At, B0); PG8_BAR; PG8_SCHED;
;             PG8_STAGE(PG8_SB(0, 1), b2 + hstepB, voffB);
;             PG8_WAIT_V(6); PG8_BAR; PG8_MMA(1, 1, At, B1); PG8_BAR;
.Lresync_y_719:
.LBB0_719:
	s_add_i32 s14, s4, 2
	s_add_u32 s15, s0, 0x80
	s_addc_u32 s5, s1, 0
	s_cmp_eq_u32 s48, s4
	s_cselect_b32 s4, s59, s15
	s_cselect_b32 s5, s57, s5
	s_cselect_b32 s95, vcc_lo, s35
	s_cselect_b32 s94, vcc_hi, s34
	v_lshl_add_u64 v[154:155], s[0:1], 0, v[202:203]
	s_add_i32 m0, s52, 0xc000
	global_load_lds_dwordx4 v[154:155], off
	v_lshl_add_u64 v[154:155], s[0:1], 0, v[204:205]
	s_add_i32 m0, s52, 0xe000
	s_nop 0
	global_load_lds_dwordx4 v[154:155], off
	s_add_i32 s8, 0, 0x10000
	v_add_u32_e32 v118, s8, v217
	ds_read_b128 v[106:109], v118
	ds_read_b128 v[110:113], v118 offset:1024
	ds_read_b128 v[114:117], v118 offset:2048
	ds_read_b128 v[118:121], v118 offset:3072
	ds_read_b128 v[122:125], v235
	ds_read_b128 v[126:129], v235 offset:1024
	ds_read_b128 v[130:133], v235 offset:2048
	ds_read_b128 v[134:137], v235 offset:3072
	ds_read_b128 v[138:141], v235 offset:4096
	ds_read_b128 v[142:145], v235 offset:5120
	ds_read_b128 v[146:149], v235 offset:6144
	ds_read_b128 v[150:153], v235 offset:7168
	s_waitcnt lgkmcnt(8)
	s_waitcnt lgkmcnt(0)
	v_mfma_f32_16x16x32_bf16 v[162:165], v[114:117], v[130:133], v[162:165]
	v_mfma_f32_16x16x32_bf16 v[94:97], v[106:109], v[138:141], v[94:97]
	v_mfma_f32_16x16x32_bf16 v[90:93], v[114:117], v[138:141], v[90:93]
	v_mfma_f32_16x16x32_bf16 v[78:81], v[106:109], v[146:149], v[78:81]
	s_barrier
	s_waitcnt lgkmcnt(0)
	s_setprio 1
	s_waitcnt lgkmcnt(0)
	v_mfma_f32_16x16x32_bf16 v[74:77], v[114:117], v[146:149], v[74:77]
	v_mfma_f32_16x16x32_bf16 v[154:157], v[106:109], v[122:125], v[190:193]
	v_mfma_f32_16x16x32_bf16 v[158:161], v[114:117], v[122:125], v[186:189]
	v_mfma_f32_16x16x32_bf16 v[166:169], v[106:109], v[130:133], v[174:177]
	v_mfma_f32_16x16x32_bf16 v[162:165], v[118:121], v[134:137], v[162:165]
	v_mfma_f32_16x16x32_bf16 v[94:97], v[110:113], v[142:145], v[94:97]
	v_mfma_f32_16x16x32_bf16 v[90:93], v[118:121], v[142:145], v[90:93]
	v_mfma_f32_16x16x32_bf16 v[78:81], v[110:113], v[150:153], v[78:81]
	v_mfma_f32_16x16x32_bf16 v[74:77], v[118:121], v[150:153], v[74:77]
	v_mfma_f32_16x16x32_bf16 v[154:157], v[110:113], v[126:129], v[154:157]
	v_mfma_f32_16x16x32_bf16 v[158:161], v[118:121], v[126:129], v[158:161]
	v_mfma_f32_16x16x32_bf16 v[166:169], v[110:113], v[134:137], v[166:169]
	s_setprio 0
	s_barrier
	s_add_i32 s8, s8, s43
	v_lshl_add_u64 v[210:211], s[94:95], 0, v[0:1]
	s_mov_b32 m0, s8
	global_load_lds_dwordx4 v[210:211], off
	v_lshl_add_u64 v[212:213], s[94:95], 0, v[200:201]
	s_add_i32 m0, s8, 0x2000
	s_nop 0
	global_load_lds_dwordx4 v[212:213], off
	s_add_i32 s9, 0, 0x14000
	v_add_u32_e32 v190, s9, v217
	ds_read_b128 v[170:173], v190
	ds_read_b128 v[174:177], v190 offset:1024
	ds_read_b128 v[186:189], v190 offset:2048
	ds_read_b128 v[190:193], v190 offset:3072
	s_waitcnt lgkmcnt(0)
	v_mfma_f32_16x16x32_bf16 v[182:185], v[170:173], v[122:125], v[182:185]
	v_mfma_f32_16x16x32_bf16 v[102:105], v[170:173], v[130:133], v[102:105]
	v_mfma_f32_16x16x32_bf16 v[98:101], v[186:189], v[130:133], v[98:101]
	v_mfma_f32_16x16x32_bf16 v[86:89], v[170:173], v[138:141], v[86:89]
	s_barrier
	s_waitcnt lgkmcnt(0)
	s_setprio 1
	s_waitcnt lgkmcnt(0)
	v_mfma_f32_16x16x32_bf16 v[82:85], v[186:189], v[138:141], v[82:85]
	v_mfma_f32_16x16x32_bf16 v[70:73], v[170:173], v[146:149], v[70:73]
	v_mfma_f32_16x16x32_bf16 v[66:69], v[186:189], v[146:149], v[66:69]
	v_mfma_f32_16x16x32_bf16 v[182:185], v[174:177], v[126:129], v[182:185]
	v_mfma_f32_16x16x32_bf16 v[122:125], v[186:189], v[122:125], v[178:181]
	v_mfma_f32_16x16x32_bf16 v[102:105], v[174:177], v[134:137], v[102:105]
	v_mfma_f32_16x16x32_bf16 v[98:101], v[190:193], v[134:137], v[98:101]
	v_mfma_f32_16x16x32_bf16 v[86:89], v[174:177], v[142:145], v[86:89]
	v_mfma_f32_16x16x32_bf16 v[82:85], v[190:193], v[142:145], v[82:85]
	v_mfma_f32_16x16x32_bf16 v[70:73], v[174:177], v[150:153], v[70:73]
	v_mfma_f32_16x16x32_bf16 v[66:69], v[190:193], v[150:153], v[66:69]
	v_mfma_f32_16x16x32_bf16 v[122:125], v[190:193], v[126:129], v[122:125]
	s_setprio 0
	s_mov_b32 m0, s52
	v_lshl_add_u64 v[214:215], s[4:5], 0, v[196:197]
	s_barrier
	global_load_lds_dwordx4 v[214:215], off
	v_lshl_add_u64 v[222:223], s[4:5], 0, v[198:199]
	s_mov_b32 m0, s53
	s_nop 0
	global_load_lds_dwordx4 v[222:223], off
	ds_read_b128 v[126:129], v235 offset:16384
	ds_read_b128 v[130:133], v235 offset:17408
	ds_read_b128 v[134:137], v235 offset:18432
	ds_read_b128 v[138:141], v235 offset:19456
	ds_read_b128 v[142:145], v235 offset:20480
	ds_read_b128 v[146:149], v235 offset:21504
	ds_read_b128 v[150:153], v235 offset:22528
	ds_read_b128 v[178:181], v235 offset:23552
	s_add_u32 s94, s94, s76
	s_addc_u32 s95, s95, s77
	s_add_i32 s8, s9, s43
	v_lshl_add_u64 v[224:225], s[94:95], 0, v[0:1]
	s_mov_b32 m0, s8
	v_lshl_add_u64 v[226:227], s[94:95], 0, v[200:201]
	global_load_lds_dwordx4 v[224:225], off
	s_add_i32 m0, s8, 0x2000
	s_nop 0
	global_load_lds_dwordx4 v[226:227], off
	s_waitcnt vmcnt(6)
	s_waitcnt lgkmcnt(0)
	v_mfma_f32_16x16x32_bf16 v[62:65], v[106:109], v[126:129], v[62:65]
	v_mfma_f32_16x16x32_bf16 v[58:61], v[114:117], v[126:129], v[58:61]
	v_mfma_f32_16x16x32_bf16 v[46:49], v[106:109], v[134:137], v[46:49]
	v_mfma_f32_16x16x32_bf16 v[42:45], v[114:117], v[134:137], v[42:45]
	s_barrier
; #define PG8_STAGE(bufoff, gbase, voff) do { _Pragma("unroll") for (int _i = 0; _i < 2; ++_i) \
;         __builtin_amdgcn_global_load_lds((const unsigned*)((const char*)(gbase) + (voff)[_i]), (LAS unsigned*)(lds + (bufoff) + ldsw + _i * 8192), 16, 0, 0); } while (0)
; #define PG8_LDA(dst, b, h) do { _Pragma("unroll") for (int m = 0; m < 4; ++m) _Pragma("unroll") for (int k = 0; k < 2; ++k) dst[m][k] = *(const LAS bf16x8*)(lds + PG8_SA(b, h) + aoff + m * 2048 + k * 1024); } while (0)
; #define PG8_LDB(dst, b, h) do { _Pragma("unroll") for (int n = 0; n < 2; ++n) _Pragma("unroll") for (int k = 0; k < 2; ++k) dst[n][k] = *(const LAS bf16x8*)(lds + PG8_SB(b, h) + boff + n * 2048 + k * 1024); } while (0)
; #define PG8_MMA(ai, bj, At, Bt) do { __builtin_amdgcn_s_setprio(1); _Pragma("unroll") for (int m = 0; m < 4; ++m) _Pragma("unroll") for (int n = 0; n < 2; ++n) _Pragma("unroll") for (int k = 0; k < 2; ++k) \
;         acc[ai][bj][m][n] = __builtin_amdgcn_mfma_f32_16x16x32_bf16(Bt[n][k], At[m][k], acc[ai][bj][m][n], 0, 0, 0); __builtin_amdgcn_s_setprio(0); } while (0)
; #define PG8_WAIT_V(n) asm volatile("s_waitcnt vmcnt(" #n ")" ::: "memory")
; #define PG8_WAIT_L(n) asm volatile("s_waitcnt lgkmcnt(" #n ")" ::: "memory")
; #define PG8_BAR __builtin_amdgcn_s_barrier()
; #define PG8_SCHED __builtin_amdgcn_sched_barrier(0)
; template <class Epi>
; __device__ __forceinline__ void gemm_phase(LAS unsigned char* lds, const Gemm g, const Sched& S, const Epi& E) {
;     ...
;             PG8_WAIT_V(6); PG8_BAR; PG8_MMA(1, 1, At, B1); PG8_BAR;
;             PG8_LDB(B0, 1, 0); PG8_SCHED; PG8_LDA(At, 1, 0); PG8_STAGE(PG8_SA(0, 1), a2 + hstepA, voffA);
;             PG8_WAIT_L(8); PG8_BAR; PG8_WAIT_L(0); PG8_MMA(0, 0, At, B0); PG8_BAR; PG8_SCHED;
;             PG8_LDB(B1, 1, 1); PG8_STAGE(PG8_SB(1, 0), b3, voffB);
;             PG8_BAR; PG8_WAIT_L(0); PG8_MMA(0, 1, At, B1); PG8_BAR;
;             PG8_LDA(At, 1, 1); PG8_STAGE(PG8_SA(1, 0), a3, voffA);
;             PG8_BAR; PG8_WAIT_L(0); PG8_MMA(1, 0, At, B0); PG8_BAR; PG8_SCHED;
	s_setprio 1
	v_mfma_f32_16x16x32_bf16 v[30:33], v[106:109], v[142:145], v[30:33]
	v_mfma_f32_16x16x32_bf16 v[26:29], v[114:117], v[142:145], v[26:29]
	v_mfma_f32_16x16x32_bf16 v[14:17], v[106:109], v[150:153], v[14:17]
	v_mfma_f32_16x16x32_bf16 v[10:13], v[114:117], v[150:153], v[10:13]
	v_mfma_f32_16x16x32_bf16 v[62:65], v[110:113], v[130:133], v[62:65]
	v_mfma_f32_16x16x32_bf16 v[58:61], v[118:121], v[130:133], v[58:61]
	v_mfma_f32_16x16x32_bf16 v[46:49], v[110:113], v[138:141], v[46:49]
	v_mfma_f32_16x16x32_bf16 v[42:45], v[118:121], v[138:141], v[42:45]
	v_mfma_f32_16x16x32_bf16 v[30:33], v[110:113], v[146:149], v[30:33]
	v_mfma_f32_16x16x32_bf16 v[26:29], v[118:121], v[146:149], v[26:29]
	v_mfma_f32_16x16x32_bf16 v[14:17], v[110:113], v[178:181], v[14:17]
	v_mfma_f32_16x16x32_bf16 v[10:13], v[118:121], v[178:181], v[10:13]
	v_mfma_f32_16x16x32_bf16 v[54:57], v[170:173], v[126:129], v[54:57]
	v_mfma_f32_16x16x32_bf16 v[50:53], v[186:189], v[126:129], v[50:53]
	v_mfma_f32_16x16x32_bf16 v[38:41], v[170:173], v[134:137], v[38:41]
	v_mfma_f32_16x16x32_bf16 v[34:37], v[186:189], v[134:137], v[34:37]
	v_mfma_f32_16x16x32_bf16 v[22:25], v[170:173], v[142:145], v[22:25]
	v_mfma_f32_16x16x32_bf16 v[18:21], v[186:189], v[142:145], v[18:21]
	v_mfma_f32_16x16x32_bf16 v[6:9], v[170:173], v[150:153], v[6:9]
	v_mfma_f32_16x16x32_bf16 v[2:5], v[186:189], v[150:153], v[2:5]
	v_mfma_f32_16x16x32_bf16 v[54:57], v[174:177], v[130:133], v[54:57]
	v_mfma_f32_16x16x32_bf16 v[50:53], v[190:193], v[130:133], v[50:53]
	v_mfma_f32_16x16x32_bf16 v[38:41], v[174:177], v[138:141], v[38:41]
	v_mfma_f32_16x16x32_bf16 v[34:37], v[190:193], v[138:141], v[34:37]
	v_mfma_f32_16x16x32_bf16 v[22:25], v[174:177], v[146:149], v[22:25]
	v_mfma_f32_16x16x32_bf16 v[18:21], v[190:193], v[146:149], v[18:21]
	v_mfma_f32_16x16x32_bf16 v[6:9], v[174:177], v[178:181], v[6:9]
	v_mfma_f32_16x16x32_bf16 v[2:5], v[190:193], v[178:181], v[2:5]
	s_setprio 0
	s_add_i32 s8, 0, 0x18000
	v_add_u32_e32 v118, s8, v217
	s_barrier
	s_add_u32 s4, s4, s40
	s_addc_u32 s5, s5, s41
	s_mov_b32 m0, s56
	v_lshl_add_u64 v[174:175], s[4:5], 0, v[196:197]
	global_load_lds_dwordx4 v[174:175], off
	v_lshl_add_u64 v[174:175], s[4:5], 0, v[198:199]
	s_mov_b32 m0, s67
	s_nop 0
	global_load_lds_dwordx4 v[174:175], off
	ds_read_b128 v[106:109], v118
	ds_read_b128 v[110:113], v118 offset:1024
	ds_read_b128 v[114:117], v118 offset:2048
	ds_read_b128 v[118:121], v118 offset:3072
	ds_read_b128 v[126:129], v235 offset:32768
	ds_read_b128 v[130:133], v235 offset:33792
	ds_read_b128 v[134:137], v235 offset:34816
	ds_read_b128 v[138:141], v235 offset:35840
	ds_read_b128 v[142:145], v235 offset:36864
	ds_read_b128 v[146:149], v235 offset:37888
	ds_read_b128 v[150:153], v235 offset:38912
	ds_read_b128 v[170:173], v235 offset:39936
	s_waitcnt lgkmcnt(8)
	s_waitcnt lgkmcnt(0)
	v_mfma_f32_16x16x32_bf16 v[154:157], v[106:109], v[126:129], v[154:157]
	v_mfma_f32_16x16x32_bf16 v[190:193], v[110:113], v[130:133], v[154:157]
	v_mfma_f32_16x16x32_bf16 v[154:157], v[114:117], v[126:129], v[158:161]
	v_mfma_f32_16x16x32_bf16 v[186:189], v[118:121], v[130:133], v[154:157]
	s_barrier
	s_waitcnt lgkmcnt(0)
	s_setprio 1
	s_waitcnt lgkmcnt(0)
	v_mfma_f32_16x16x32_bf16 v[154:157], v[106:109], v[134:137], v[166:169]
	v_mfma_f32_16x16x32_bf16 v[174:177], v[110:113], v[138:141], v[154:157]
	v_mfma_f32_16x16x32_bf16 v[154:157], v[114:117], v[134:137], v[162:165]
	v_mfma_f32_16x16x32_bf16 v[94:97], v[106:109], v[142:145], v[94:97]
	v_mfma_f32_16x16x32_bf16 v[90:93], v[114:117], v[142:145], v[90:93]
	v_mfma_f32_16x16x32_bf16 v[78:81], v[106:109], v[150:153], v[78:81]
	v_mfma_f32_16x16x32_bf16 v[74:77], v[114:117], v[150:153], v[74:77]
	v_mfma_f32_16x16x32_bf16 v[162:165], v[118:121], v[138:141], v[154:157]
	v_mfma_f32_16x16x32_bf16 v[94:97], v[110:113], v[146:149], v[94:97]
	v_mfma_f32_16x16x32_bf16 v[90:93], v[118:121], v[146:149], v[90:93]
	v_mfma_f32_16x16x32_bf16 v[78:81], v[110:113], v[170:173], v[78:81]
	v_mfma_f32_16x16x32_bf16 v[74:77], v[118:121], v[170:173], v[74:77]
	s_setprio 0
	s_barrier
	s_add_i32 s5, s8, s43
	v_lshl_add_u64 v[178:179], v[210:211], 0, s[60:61]
	s_mov_b32 m0, s5
	s_nop 0
	global_load_lds_dwordx4 v[178:179], off
	v_lshl_add_u64 v[178:179], v[212:213], 0, s[60:61]
	s_add_i32 m0, s5, 0x2000
	s_nop 0
	global_load_lds_dwordx4 v[178:179], off
	s_add_i32 s4, 0, 0x1c000
	v_add_u32_e32 v178, s4, v217
	ds_read_b128 v[154:157], v178
	ds_read_b128 v[158:161], v178 offset:1024
	ds_read_b128 v[166:169], v178 offset:2048
	ds_read_b128 v[206:209], v178 offset:3072
	s_waitcnt lgkmcnt(0)
	v_mfma_f32_16x16x32_bf16 v[178:181], v[154:157], v[126:129], v[182:185]
	v_mfma_f32_16x16x32_bf16 v[122:125], v[166:169], v[126:129], v[122:125]
	v_mfma_f32_16x16x32_bf16 v[102:105], v[154:157], v[134:137], v[102:105]
	v_mfma_f32_16x16x32_bf16 v[98:101], v[166:169], v[134:137], v[98:101]
	s_barrier
; #define PG8_STAGE(bufoff, gbase, voff) do { _Pragma("unroll") for (int _i = 0; _i < 2; ++_i) \
;         __builtin_amdgcn_global_load_lds((const unsigned*)((const char*)(gbase) + (voff)[_i]), (LAS unsigned*)(lds + (bufoff) + ldsw + _i * 8192), 16, 0, 0); } while (0)
; #define PG8_LDA(dst, b, h) do { _Pragma("unroll") for (int m = 0; m < 4; ++m) _Pragma("unroll") for (int k = 0; k < 2; ++k) dst[m][k] = *(const LAS bf16x8*)(lds + PG8_SA(b, h) + aoff + m * 2048 + k * 1024); } while (0)
; #define PG8_MMA(ai, bj, At, Bt) do { __builtin_amdgcn_s_setprio(1); _Pragma("unroll") for (int m = 0; m < 4; ++m) _Pragma("unroll") for (int n = 0; n < 2; ++n) _Pragma("unroll") for (int k = 0; k < 2; ++k) \
;         acc[ai][bj][m][n] = __builtin_amdgcn_mfma_f32_16x16x32_bf16(Bt[n][k], At[m][k], acc[ai][bj][m][n], 0, 0, 0); __builtin_amdgcn_s_setprio(0); } while (0)
; #define PG8_WAIT_V(n) asm volatile("s_waitcnt vmcnt(" #n ")" ::: "memory")
; #define PG8_WAIT_L(n) asm volatile("s_waitcnt lgkmcnt(" #n ")" ::: "memory")
; #define PG8_BAR __builtin_amdgcn_s_barrier()
; #define PG8_SCHED __builtin_amdgcn_sched_barrier(0)
; template <class Epi>
; __device__ __forceinline__ void gemm_phase(LAS unsigned char* lds, const Gemm g, const Sched& S, const Epi& E) {
;     ...
;             PG8_LDA(At, 1, 1); PG8_STAGE(PG8_SA(1, 0), a3, voffA);
;             PG8_BAR; PG8_WAIT_L(0); PG8_MMA(1, 0, At, B0); PG8_BAR; PG8_SCHED;
;             PG8_STAGE(PG8_SB(1, 1), b3 + hstepB, voffB);
;             PG8_WAIT_V(6); PG8_BAR; PG8_MMA(1, 1, At, B1); PG8_BAR;
;         }
	s_waitcnt lgkmcnt(0)
	s_setprio 1
	s_waitcnt lgkmcnt(0)
	v_mfma_f32_16x16x32_bf16 v[86:89], v[154:157], v[142:145], v[86:89]
	v_mfma_f32_16x16x32_bf16 v[82:85], v[166:169], v[142:145], v[82:85]
	v_mfma_f32_16x16x32_bf16 v[70:73], v[154:157], v[150:153], v[70:73]
	v_mfma_f32_16x16x32_bf16 v[66:69], v[166:169], v[150:153], v[66:69]
	v_mfma_f32_16x16x32_bf16 v[182:185], v[158:161], v[130:133], v[178:181]
	v_mfma_f32_16x16x32_bf16 v[178:181], v[206:209], v[130:133], v[122:125]
	v_mfma_f32_16x16x32_bf16 v[102:105], v[158:161], v[138:141], v[102:105]
	v_mfma_f32_16x16x32_bf16 v[98:101], v[206:209], v[138:141], v[98:101]
	v_mfma_f32_16x16x32_bf16 v[86:89], v[158:161], v[146:149], v[86:89]
	v_mfma_f32_16x16x32_bf16 v[82:85], v[206:209], v[146:149], v[82:85]
	v_mfma_f32_16x16x32_bf16 v[70:73], v[158:161], v[170:173], v[70:73]
	v_mfma_f32_16x16x32_bf16 v[66:69], v[206:209], v[170:173], v[66:69]
	s_setprio 0
	s_mov_b32 m0, s51
	v_lshl_add_u64 v[170:171], v[214:215], 0, s[60:61]
	s_barrier
	global_load_lds_dwordx4 v[170:171], off
	v_lshl_add_u64 v[170:171], v[222:223], 0, s[60:61]
	s_mov_b32 m0, s2
	s_nop 0
	global_load_lds_dwordx4 v[170:171], off
	ds_read_b128 v[122:125], v235 offset:49152
	ds_read_b128 v[126:129], v235 offset:50176
	ds_read_b128 v[130:133], v235 offset:51200
	ds_read_b128 v[134:137], v235 offset:52224
	ds_read_b128 v[138:141], v235 offset:53248
	ds_read_b128 v[142:145], v235 offset:54272
	ds_read_b128 v[146:149], v235 offset:55296
	ds_read_b128 v[150:153], v235 offset:56320
	s_add_i32 s4, s4, s43
	v_lshl_add_u64 v[170:171], v[224:225], 0, s[60:61]
	s_mov_b32 m0, s4
	s_nop 0
	global_load_lds_dwordx4 v[170:171], off
	v_lshl_add_u64 v[170:171], v[226:227], 0, s[60:61]
	s_add_i32 m0, s4, 0x2000
	s_nop 0
	global_load_lds_dwordx4 v[170:171], off
	s_waitcnt vmcnt(6)
	s_waitcnt lgkmcnt(0)
	v_mfma_f32_16x16x32_bf16 v[62:65], v[106:109], v[122:125], v[62:65]
	v_mfma_f32_16x16x32_bf16 v[58:61], v[114:117], v[122:125], v[58:61]
	v_mfma_f32_16x16x32_bf16 v[46:49], v[106:109], v[130:133], v[46:49]
	v_mfma_f32_16x16x32_bf16 v[42:45], v[114:117], v[130:133], v[42:45]
	s_barrier
	s_setprio 1
	v_mfma_f32_16x16x32_bf16 v[30:33], v[106:109], v[138:141], v[30:33]
	v_mfma_f32_16x16x32_bf16 v[26:29], v[114:117], v[138:141], v[26:29]
	v_mfma_f32_16x16x32_bf16 v[14:17], v[106:109], v[146:149], v[14:17]
	v_mfma_f32_16x16x32_bf16 v[10:13], v[114:117], v[146:149], v[10:13]
	v_mfma_f32_16x16x32_bf16 v[62:65], v[110:113], v[126:129], v[62:65]
	v_mfma_f32_16x16x32_bf16 v[58:61], v[118:121], v[126:129], v[58:61]
	v_mfma_f32_16x16x32_bf16 v[46:49], v[110:113], v[134:137], v[46:49]
	v_mfma_f32_16x16x32_bf16 v[42:45], v[118:121], v[134:137], v[42:45]
	v_mfma_f32_16x16x32_bf16 v[30:33], v[110:113], v[142:145], v[30:33]
	v_mfma_f32_16x16x32_bf16 v[26:29], v[118:121], v[142:145], v[26:29]
	v_mfma_f32_16x16x32_bf16 v[14:17], v[110:113], v[150:153], v[14:17]
	v_mfma_f32_16x16x32_bf16 v[10:13], v[118:121], v[150:153], v[10:13]
	v_mfma_f32_16x16x32_bf16 v[54:57], v[154:157], v[122:125], v[54:57]
	v_mfma_f32_16x16x32_bf16 v[50:53], v[166:169], v[122:125], v[50:53]
	v_mfma_f32_16x16x32_bf16 v[38:41], v[154:157], v[130:133], v[38:41]
	v_mfma_f32_16x16x32_bf16 v[34:37], v[166:169], v[130:133], v[34:37]
	v_mfma_f32_16x16x32_bf16 v[22:25], v[154:157], v[138:141], v[22:25]
	v_mfma_f32_16x16x32_bf16 v[18:21], v[166:169], v[138:141], v[18:21]
	v_mfma_f32_16x16x32_bf16 v[6:9], v[154:157], v[146:149], v[6:9]
	v_mfma_f32_16x16x32_bf16 v[2:5], v[166:169], v[146:149], v[2:5]
	v_mfma_f32_16x16x32_bf16 v[54:57], v[158:161], v[126:129], v[54:57]
	v_mfma_f32_16x16x32_bf16 v[50:53], v[206:209], v[126:129], v[50:53]
	v_mfma_f32_16x16x32_bf16 v[38:41], v[158:161], v[134:137], v[38:41]
	v_mfma_f32_16x16x32_bf16 v[34:37], v[206:209], v[134:137], v[34:37]
	v_mfma_f32_16x16x32_bf16 v[22:25], v[158:161], v[142:145], v[22:25]
	v_mfma_f32_16x16x32_bf16 v[18:21], v[206:209], v[142:145], v[18:21]
	v_mfma_f32_16x16x32_bf16 v[6:9], v[158:161], v[150:153], v[6:9]
	v_mfma_f32_16x16x32_bf16 v[2:5], v[206:209], v[150:153], v[2:5]
	s_setprio 0
	s_add_u32 s0, s0, 0x100
	s_addc_u32 s1, s1, 0
	s_add_u32 s34, s34, 0x100
	s_addc_u32 s35, s35, 0
	s_cmp_ge_u32 s14, s73
	s_mov_b32 s4, s14
	s_barrier
	s_cbranch_scc0 .LBB0_719
	v_readfirstlane_b32 s98, v219
	s_nop 1
	s_bitcmp1_b32 s98, 8
	s_cbranch_scc1 .Lresync_x_719
	s_barrier
